# whole tile at s_setprio 1 except selected-loop stages where the wave has no selected block
# speedup vs baseline: 1.0019x; 1.0019x over previous
.LBB0_638:
	s_setprio 1
	s_mov_b64 s[2:3], 0x2000
	v_lshl_add_u64 v[192:193], v[202:203], 0, s[2:3]
	s_mov_b64 s[2:3], 0x4000
	v_lshl_add_u64 v[194:195], v[202:203], 0, s[2:3]
	s_mov_b64 s[2:3], 0x6000
	v_lshl_add_u64 v[190:191], v[202:203], 0, s[2:3]
	global_load_dword v104, v[210:211], off offset:36
	global_load_dwordx4 v[106:109], v[202:203], off
	global_load_dwordx4 v[110:113], v[202:203], off offset:64
	global_load_dwordx4 v[114:117], v[202:203], off offset:128
	global_load_dwordx4 v[118:121], v[202:203], off offset:192
	global_load_dword v105, v[212:213], off offset:36
	global_load_dwordx4 v[122:125], v[192:193], off
	global_load_dwordx4 v[130:133], v[192:193], off offset:64
	global_load_dwordx4 v[134:137], v[192:193], off offset:128
	global_load_dwordx4 v[158:161], v[192:193], off offset:192
	global_load_dword v126, v[196:197], off offset:36
	global_load_dwordx4 v[162:165], v[194:195], off
	global_load_dwordx4 v[166:169], v[194:195], off offset:64
	global_load_dwordx4 v[170:173], v[194:195], off offset:128
	global_load_dwordx4 v[174:177], v[194:195], off offset:192
	global_load_dword v127, v[200:201], off offset:36
	global_load_dwordx4 v[178:181], v[190:191], off
	global_load_dwordx4 v[182:185], v[190:191], off offset:64
	global_load_dwordx4 v[186:189], v[190:191], off offset:128
	global_load_dwordx4 v[248:251], v[190:191], off offset:192
	v_add_f32_e32 v0, 0, v154
	v_add_f32_e32 v4, 0, v150
	v_add_f32_e32 v5, 0, v142
	v_add_f32_e32 v6, 0, v146
	s_mov_b64 s[40:41], 0
	s_waitcnt vmcnt(19)
	v_mul_f32_e32 v1, 0xbfb8aa3b, v104
	v_exp_f32_e32 v1, v1
	s_nop 0
	v_add_f32_e32 v1, 1.0, v1
	v_rcp_f32_e32 v1, v1
	s_nop 0
	v_div_scale_f32 v2, s[2:3], v0, v0, v1
	v_rcp_f32_e32 v3, v2
	s_nop 0
	v_fma_f32 v7, -v2, v3, 1.0
	v_fmac_f32_e32 v3, v7, v3
	v_div_scale_f32 v7, vcc, v1, v0, v1
	v_mul_f32_e32 v56, v7, v3
	v_fma_f32 v57, -v2, v56, v7
	v_fmac_f32_e32 v56, v57, v3
	v_fma_f32 v2, -v2, v56, v7
	v_div_fmas_f32 v2, v2, v3, v56
	v_div_fixup_f32 v2, v2, v0, v1
	v_lshl_add_u64 v[0:1], s[36:37], 0, v[214:215]
	v_lshl_add_u64 v[56:57], v[0:1], 0, v[128:129]
	v_lshlrev_b32_e32 v0, 1, v241
	v_mov_b32_e32 v1, v129
	v_lshl_add_u64 v[68:69], v[56:57], 0, v[0:1]
	s_waitcnt vmcnt(18)
	v_pk_fma_f32 v[56:57], v[100:101], v[2:3], v[106:107] op_sel_hi:[1,0,1]
	v_pk_fma_f32 v[58:59], v[102:103], v[2:3], v[108:109] op_sel_hi:[1,0,1]
	v_cvt_pk_bf16_f32 v56, v56, v57
	v_cvt_pk_bf16_f32 v57, v58, v59
	global_store_dwordx2 v[68:69], v[56:57], off offset:512
	s_waitcnt vmcnt(18)
	v_pk_fma_f32 v[56:57], v[72:73], v[2:3], v[110:111] op_sel_hi:[1,0,1]
	v_pk_fma_f32 v[58:59], v[74:75], v[2:3], v[112:113] op_sel_hi:[1,0,1]
	v_cvt_pk_bf16_f32 v56, v56, v57
	v_cvt_pk_bf16_f32 v57, v58, v59
	global_store_dwordx2 v[68:69], v[56:57], off offset:544
	s_waitcnt vmcnt(18)
	v_pk_fma_f32 v[56:57], v[64:65], v[2:3], v[114:115] op_sel_hi:[1,0,1]
	v_pk_fma_f32 v[58:59], v[66:67], v[2:3], v[116:117] op_sel_hi:[1,0,1]
	v_cvt_pk_bf16_f32 v56, v56, v57
	v_cvt_pk_bf16_f32 v57, v58, v59
	global_store_dwordx2 v[68:69], v[56:57], off offset:576
	s_waitcnt vmcnt(18)
	v_pk_fma_f32 v[56:57], v[60:61], v[2:3], v[118:119] op_sel_hi:[1,0,1]
	v_pk_fma_f32 v[2:3], v[62:63], v[2:3], v[120:121] op_sel_hi:[1,0,1]
	v_cvt_pk_bf16_f32 v56, v56, v57
	v_cvt_pk_bf16_f32 v57, v2, v3
	global_store_dwordx2 v[68:69], v[56:57], off offset:608
	s_waitcnt vmcnt(18)
	v_mul_f32_e32 v2, 0xbfb8aa3b, v105
	v_exp_f32_e32 v2, v2
	s_nop 0
	v_add_f32_e32 v2, 1.0, v2
	v_rcp_f32_e32 v2, v2
	s_nop 0
	v_div_scale_f32 v3, s[2:3], v4, v4, v2
	v_rcp_f32_e32 v7, v3
	s_nop 0
	v_fma_f32 v56, -v3, v7, 1.0
	v_fmac_f32_e32 v7, v56, v7
	v_div_scale_f32 v56, vcc, v2, v4, v2
	v_mul_f32_e32 v57, v56, v7
	v_fma_f32 v58, -v3, v57, v56
	v_fmac_f32_e32 v57, v58, v7
	v_fma_f32 v3, -v3, v57, v56
	v_div_fmas_f32 v3, v3, v7, v57
	v_div_fixup_f32 v4, v3, v4, v2
	v_lshl_add_u64 v[2:3], s[36:37], 0, v[216:217]
	v_lshl_add_u64 v[2:3], v[2:3], 0, v[128:129]
	v_lshl_add_u64 v[2:3], v[2:3], 0, v[0:1]
	s_waitcnt vmcnt(17)
	v_pk_fma_f32 v[52:53], v[52:53], v[4:5], v[122:123] op_sel_hi:[1,0,1]
	v_pk_fma_f32 v[54:55], v[54:55], v[4:5], v[124:125] op_sel_hi:[1,0,1]
	v_cvt_pk_bf16_f32 v52, v52, v53
	v_cvt_pk_bf16_f32 v53, v54, v55
	global_store_dwordx2 v[2:3], v[52:53], off offset:512
	s_waitcnt vmcnt(17)
	v_pk_fma_f32 v[48:49], v[48:49], v[4:5], v[130:131] op_sel_hi:[1,0,1]
	v_pk_fma_f32 v[50:51], v[50:51], v[4:5], v[132:133] op_sel_hi:[1,0,1]
	v_cvt_pk_bf16_f32 v48, v48, v49
	v_cvt_pk_bf16_f32 v49, v50, v51
	global_store_dwordx2 v[2:3], v[48:49], off offset:544
	s_waitcnt vmcnt(17)
	v_pk_fma_f32 v[44:45], v[44:45], v[4:5], v[134:135] op_sel_hi:[1,0,1]
	v_pk_fma_f32 v[46:47], v[46:47], v[4:5], v[136:137] op_sel_hi:[1,0,1]
	v_cvt_pk_bf16_f32 v44, v44, v45
	v_cvt_pk_bf16_f32 v45, v46, v47
	global_store_dwordx2 v[2:3], v[44:45], off offset:576
	s_waitcnt vmcnt(17)
	v_pk_fma_f32 v[40:41], v[40:41], v[4:5], v[158:159] op_sel_hi:[1,0,1]
	v_pk_fma_f32 v[42:43], v[42:43], v[4:5], v[160:161] op_sel_hi:[1,0,1]
	v_cvt_pk_bf16_f32 v40, v40, v41
	v_cvt_pk_bf16_f32 v41, v42, v43
	global_store_dwordx2 v[2:3], v[40:41], off offset:608
	s_waitcnt vmcnt(17)
	v_mul_f32_e32 v2, 0xbfb8aa3b, v126
	v_exp_f32_e32 v2, v2
	s_nop 0
	v_add_f32_e32 v2, 1.0, v2
	v_rcp_f32_e32 v2, v2
	s_nop 0
	v_div_scale_f32 v3, s[2:3], v6, v6, v2
	v_rcp_f32_e32 v4, v3
	s_nop 0
	v_fma_f32 v7, -v3, v4, 1.0
	v_fmac_f32_e32 v4, v7, v4
	v_div_scale_f32 v7, vcc, v2, v6, v2
	v_mul_f32_e32 v40, v7, v4
	v_fma_f32 v41, -v3, v40, v7
	v_fmac_f32_e32 v40, v41, v4
	v_fma_f32 v3, -v3, v40, v7
	v_div_fmas_f32 v3, v3, v4, v40
	v_div_fixup_f32 v2, v3, v6, v2
	v_lshl_add_u64 v[6:7], s[36:37], 0, v[204:205]
	v_lshl_add_u64 v[6:7], v[6:7], 0, v[128:129]
	v_lshl_add_u64 v[6:7], v[6:7], 0, v[0:1]
	s_waitcnt vmcnt(16)
	v_pk_fma_f32 v[36:37], v[36:37], v[2:3], v[162:163] op_sel_hi:[1,0,1]
	v_pk_fma_f32 v[38:39], v[38:39], v[2:3], v[164:165] op_sel_hi:[1,0,1]
	v_cvt_pk_bf16_f32 v36, v36, v37
	v_cvt_pk_bf16_f32 v37, v38, v39
	global_store_dwordx2 v[6:7], v[36:37], off offset:512
	s_waitcnt vmcnt(16)
	v_pk_fma_f32 v[32:33], v[32:33], v[2:3], v[166:167] op_sel_hi:[1,0,1]
	v_pk_fma_f32 v[34:35], v[34:35], v[2:3], v[168:169] op_sel_hi:[1,0,1]
	v_cvt_pk_bf16_f32 v32, v32, v33
	v_cvt_pk_bf16_f32 v33, v34, v35
	global_store_dwordx2 v[6:7], v[32:33], off offset:544
	s_waitcnt vmcnt(16)
	v_pk_fma_f32 v[28:29], v[28:29], v[2:3], v[170:171] op_sel_hi:[1,0,1]
	v_pk_fma_f32 v[30:31], v[30:31], v[2:3], v[172:173] op_sel_hi:[1,0,1]
	v_cvt_pk_bf16_f32 v28, v28, v29
	v_cvt_pk_bf16_f32 v29, v30, v31
	global_store_dwordx2 v[6:7], v[28:29], off offset:576
	s_waitcnt vmcnt(16)
	v_pk_fma_f32 v[24:25], v[24:25], v[2:3], v[174:175] op_sel_hi:[1,0,1]
	v_pk_fma_f32 v[2:3], v[26:27], v[2:3], v[176:177] op_sel_hi:[1,0,1]
	v_cvt_pk_bf16_f32 v24, v24, v25
	v_cvt_pk_bf16_f32 v25, v2, v3
	global_store_dwordx2 v[6:7], v[24:25], off offset:608
	s_waitcnt vmcnt(16)
	v_mul_f32_e32 v2, 0xbfb8aa3b, v127
	v_exp_f32_e32 v2, v2
	s_nop 0
	v_add_f32_e32 v2, 1.0, v2
	v_rcp_f32_e32 v2, v2
	s_nop 0
	v_div_scale_f32 v3, s[2:3], v5, v5, v2
	v_rcp_f32_e32 v4, v3
	s_nop 0
	v_fma_f32 v6, -v3, v4, 1.0
	v_fmac_f32_e32 v4, v6, v4
	v_div_scale_f32 v6, vcc, v2, v5, v2
	v_mul_f32_e32 v7, v6, v4
	v_fma_f32 v24, -v3, v7, v6
	v_fmac_f32_e32 v7, v24, v4
	v_fma_f32 v3, -v3, v7, v6
	v_div_fmas_f32 v3, v3, v4, v7
	v_div_fixup_f32 v2, v3, v5, v2
	v_lshl_add_u64 v[4:5], s[36:37], 0, v[206:207]
	v_lshl_add_u64 v[4:5], v[4:5], 0, v[128:129]
	v_lshl_add_u64 v[0:1], v[4:5], 0, v[0:1]
	s_waitcnt vmcnt(15)
	v_pk_fma_f32 v[4:5], v[20:21], v[2:3], v[178:179] op_sel_hi:[1,0,1]
	v_pk_fma_f32 v[6:7], v[22:23], v[2:3], v[180:181] op_sel_hi:[1,0,1]
	v_cvt_pk_bf16_f32 v4, v4, v5
	v_cvt_pk_bf16_f32 v5, v6, v7
	global_store_dwordx2 v[0:1], v[4:5], off offset:512
	s_waitcnt vmcnt(15)
	v_pk_fma_f32 v[4:5], v[16:17], v[2:3], v[182:183] op_sel_hi:[1,0,1]
	v_pk_fma_f32 v[6:7], v[18:19], v[2:3], v[184:185] op_sel_hi:[1,0,1]
	v_cvt_pk_bf16_f32 v4, v4, v5
	v_cvt_pk_bf16_f32 v5, v6, v7
	global_store_dwordx2 v[0:1], v[4:5], off offset:544
	s_waitcnt vmcnt(15)
	v_pk_fma_f32 v[4:5], v[12:13], v[2:3], v[186:187] op_sel_hi:[1,0,1]
	v_pk_fma_f32 v[6:7], v[14:15], v[2:3], v[188:189] op_sel_hi:[1,0,1]
	v_cvt_pk_bf16_f32 v4, v4, v5
	v_cvt_pk_bf16_f32 v5, v6, v7
	global_store_dwordx2 v[0:1], v[4:5], off offset:576
	s_waitcnt vmcnt(15)
	v_pk_fma_f32 v[4:5], v[8:9], v[2:3], v[248:249] op_sel_hi:[1,0,1]
	v_pk_fma_f32 v[2:3], v[10:11], v[2:3], v[250:251] op_sel_hi:[1,0,1]
	v_cvt_pk_bf16_f32 v4, v4, v5
	v_cvt_pk_bf16_f32 v5, v2, v3
	global_store_dwordx2 v[0:1], v[4:5], off offset:608

.LBB0_644:
	s_or_b64 exec, exec, s[40:41]
	s_waitcnt lgkmcnt(0)
	s_barrier
	ds_read_b32 v0, v226
	s_movk_i32 s2, 0x3ff
	s_mov_b64 s[40:41], -1
	s_waitcnt lgkmcnt(0)
	v_cmp_lt_i32_e32 vcc, s2, v0
	v_readfirstlane_b32 s26, v0
	s_cbranch_vccnz .LBB0_639
	s_setprio 1
	s_ashr_i32 s64, s26, 2
	v_mov_b32_e32 v10, v218
	s_sub_i32 s69, 0xff, s64
	s_and_b32 s45, s26, 1
	s_lshl_b32 s2, s26, 13
	v_ashrrev_i32_e32 v0, 2, v10
	v_and_b32_e32 v240, -16, v0
	s_and_b32 s84, s2, 0x4000
	s_lshl_b32 s2, s69, 6
	s_lshl_b32 s3, s45, 2
	v_add_u32_e32 v198, s2, v240
	v_and_or_b32 v214, v10, 3, s3
	s_add_i32 s2, s84, s2
	s_mov_b32 s3, s85
	v_ashrrev_i32_e32 v1, 31, v0
	v_lshl_add_u64 v[2:3], s[2:3], 0, v[0:1]
	v_lshlrev_b32_e32 v1, 3, v10
	v_and_b32_e32 v128, 24, v1
	v_ashrrev_i32_e32 v199, 31, v198
	v_lshlrev_b64 v[2:3], 6, v[2:3]
	v_lshl_or_b32 v11, v0, 5, v128
	v_lshl_add_u64 v[200:201], v[198:199], 0, s[84:85]
	v_bfe_u32 v0, v10, 2, 2
	v_lshl_add_u64 v[2:3], s[56:57], 0, v[2:3]
	s_lshl_b32 s2, s45, 5
	v_or_b32_e32 v200, v200, v0
	v_mov_b64_e32 v[0:1], s[52:53]
	v_lshl_add_u64 v[2:3], v[2:3], 0, s[2:3]
	v_mad_u64_u32 v[18:19], s[2:3], v200, s10, v[0:1]
	v_bfe_u32 v241, v10, 4, 2
	v_lshl_add_u64 v[2:3], v[2:3], 0, v[128:129]
	v_mad_i32_i24 v19, v201, s10, v19
	v_lshlrev_b32_e32 v128, 7, v214
	v_lshl_add_u64 v[0:1], v[18:19], 0, v[128:129]
	v_lshlrev_b32_e32 v202, 4, v241
	v_mov_b32_e32 v203, v129
	v_lshl_add_u64 v[4:5], v[0:1], 0, v[202:203]
	global_load_dwordx2 v[2:3], v[2:3], off
	s_mov_b64 s[2:3], 0x6000
	v_lshlrev_b64 v[124:125], 6, v[200:201]
	v_lshl_add_u64 v[124:125], s[54:55], 0, v[124:125]
	global_load_dwordx4 v[40:43], v[4:5], off offset:2112
	global_load_dwordx4 v[44:47], v[0:1], off offset:2048
	global_load_dwordx4 v[48:51], v[0:1], off offset:2064
	global_load_dwordx4 v[52:55], v[124:125], off offset:48
	global_load_dwordx4 v[56:59], v[124:125], off offset:16
	global_load_dwordx4 v[60:63], v[124:125], off offset:32
	global_load_dwordx4 v[64:67], v[124:125], off
	global_load_dwordx4 v[68:71], v[4:5], off offset:2048
	v_lshl_add_u64 v[36:37], v[0:1], 0, s[2:3]
	v_lshl_add_u64 v[38:39], v[4:5], 0, s[2:3]
	global_load_dwordx4 v[76:79], v[38:39], off offset:2112
	global_load_dwordx4 v[80:83], v[36:37], off offset:2048
	global_load_dwordx4 v[84:87], v[36:37], off offset:2064
	global_load_dwordx4 v[88:91], v[124:125], off offset:304
	global_load_dwordx4 v[92:95], v[124:125], off offset:272
	global_load_dwordx4 v[96:99], v[124:125], off offset:288
	global_load_dwordx4 v[116:119], v[124:125], off offset:256
	global_load_dwordx4 v[120:123], v[38:39], off offset:2048
	v_lshl_add_u64 v[36:37], v[36:37], 0, s[2:3]
	v_lshl_add_u64 v[38:39], v[38:39], 0, s[2:3]
	global_load_dwordx4 v[130:133], v[38:39], off offset:2112
	global_load_dwordx4 v[134:137], v[36:37], off offset:2048
	global_load_dwordx4 v[138:141], v[36:37], off offset:2064
	global_load_dwordx4 v[142:145], v[124:125], off offset:560
	global_load_dwordx4 v[146:149], v[124:125], off offset:528
	global_load_dwordx4 v[150:153], v[124:125], off offset:544
	global_load_dwordx4 v[154:157], v[124:125], off offset:512
	global_load_dwordx4 v[158:161], v[38:39], off offset:2048
	v_lshl_add_u64 v[36:37], v[36:37], 0, s[2:3]
	v_lshl_add_u64 v[38:39], v[38:39], 0, s[2:3]
	global_load_dwordx4 v[162:165], v[38:39], off offset:2112
	global_load_dwordx4 v[166:169], v[36:37], off offset:2048
	global_load_dwordx4 v[170:173], v[36:37], off offset:2064
	global_load_dwordx4 v[174:177], v[124:125], off offset:816
	global_load_dwordx4 v[178:181], v[124:125], off offset:784
	global_load_dwordx4 v[182:185], v[124:125], off offset:800
	global_load_dwordx4 v[186:189], v[124:125], off offset:768
	global_load_dwordx4 v[190:193], v[38:39], off offset:2048
	v_and_b32_e32 v12, 15, v10
	v_and_b32_e32 v10, 0xfffffc0, v10
	v_mul_lo_u32 v199, v10, s31
	v_add_u32_e32 v10, 0x11000, v11
	v_mul_u32_u24_e32 v14, 0x90, v12
	v_cmp_gt_u32_e64 s[42:43], 2, v241
	v_cmp_eq_u32_e32 vcc, 0, v241
	v_add3_u32 v22, v199, v14, v202
	s_waitcnt vmcnt(32)
	ds_write_b64 v10, v[2:3]
	s_waitcnt vmcnt(24)
	v_and_b32_e32 v3, 0xffff0000, v40
	v_lshlrev_b32_e32 v2, 16, v40
	v_and_b32_e32 v11, 0xffff0000, v41
	v_lshlrev_b32_e32 v10, 16, v41
	v_and_b32_e32 v7, 0xffff0000, v42
	v_lshlrev_b32_e32 v6, 16, v42
	v_and_b32_e32 v13, 0xffff0000, v43
	v_lshlrev_b32_e32 v12, 16, v43
	v_pk_mul_f32 v[2:3], v[2:3], s[30:31] op_sel_hi:[1,0]
	v_pk_mul_f32 v[8:9], v[10:11], s[30:31] op_sel_hi:[1,0]
	v_pk_mul_f32 v[10:11], v[6:7], s[30:31] op_sel_hi:[1,0]
	v_pk_mul_f32 v[12:13], v[12:13], s[30:31] op_sel_hi:[1,0]
	v_cvt_pk_bf16_f32 v6, v2, v3
	v_cvt_pk_bf16_f32 v7, v8, v9
	v_cvt_pk_bf16_f32 v8, v10, v11
	v_cvt_pk_bf16_f32 v9, v12, v13
	ds_write_b128 v22, v[6:9] offset:32832
	s_and_saveexec_b64 s[2:3], s[42:43]
	s_xor_b64 s[40:41], exec, s[2:3]
	s_cbranch_execz .LBB0_647
	v_lshlrev_b64 v[0:1], 6, v[200:201]
	v_lshl_add_u64 v[0:1], s[54:55], 0, v[0:1]
	v_and_b32_e32 v21, 0xffff0000, v44
	v_and_b32_e32 v33, 0xffff0000, v48
	v_lshlrev_b32_e32 v32, 16, v48
	v_lshlrev_b32_e32 v20, 16, v44
	v_pk_mul_f32 v[0:1], v[60:61], v[32:33]
	v_lshlrev_b32_e32 v10, 16, v49
	v_pk_fma_f32 v[0:1], v[64:65], v[20:21], v[0:1] neg_lo:[0,0,1] neg_hi:[0,0,1]
	v_pk_mul_f32 v[28:29], v[64:65], v[32:33]
	s_nop 0
	v_pk_fma_f32 v[20:21], v[60:61], v[20:21], v[28:29]
	s_nop 0
	v_cndmask_b32_e32 v1, v21, v1, vcc
	v_cndmask_b32_e32 v0, v20, v0, vcc
	v_and_b32_e32 v21, 0xffff0000, v45
	v_lshlrev_b32_e32 v20, 16, v45
	v_and_b32_e32 v11, 0xffff0000, v49
	v_pk_mul_f32 v[14:15], v[62:63], v[10:11]
	v_pk_mul_f32 v[0:1], v[0:1], s[30:31] op_sel_hi:[1,0]
	v_pk_fma_f32 v[14:15], v[66:67], v[20:21], v[14:15] neg_lo:[0,0,1] neg_hi:[0,0,1]
	v_pk_mul_f32 v[20:21], v[62:63], v[20:21]
	v_cvt_pk_bf16_f32 v0, v0, v1
	v_pk_fma_f32 v[10:11], v[66:67], v[10:11], v[20:21]
	s_nop 0
	v_cndmask_b32_e32 v11, v11, v15, vcc
	v_cndmask_b32_e32 v10, v10, v14, vcc
	v_pk_mul_f32 v[10:11], v[10:11], s[30:31] op_sel_hi:[1,0]
	v_and_b32_e32 v15, 0xffff0000, v50
	v_cvt_pk_bf16_f32 v1, v10, v11
	v_and_b32_e32 v11, 0xffff0000, v46
	v_lshlrev_b32_e32 v10, 16, v46
	v_lshlrev_b32_e32 v14, 16, v50
	v_pk_mul_f32 v[20:21], v[52:53], v[14:15]
	v_pk_mul_f32 v[6:7], v[52:53], v[10:11]
	v_pk_fma_f32 v[20:21], v[56:57], v[10:11], v[20:21] neg_lo:[0,0,1] neg_hi:[0,0,1]
	v_pk_fma_f32 v[2:3], v[56:57], v[14:15], v[6:7]
	v_lshlrev_b32_e32 v7, 16, v51
	v_cndmask_b32_e32 v3, v3, v21, vcc
	v_cndmask_b32_e32 v2, v2, v20, vcc
	v_lshlrev_b32_e32 v6, 16, v47
	v_mov_b32_e32 v10, v58
	v_mov_b32_e32 v11, v54
	v_pk_mul_f32 v[2:3], v[2:3], s[30:31] op_sel_hi:[1,0]
	v_pk_mul_f32 v[10:11], v[10:11], v[6:7]
	v_cvt_pk_bf16_f32 v2, v2, v3
	v_sub_f32_e32 v3, v10, v11
	v_mov_b32_e32 v10, v54
	v_mov_b32_e32 v11, v58
	v_pk_mul_f32 v[6:7], v[10:11], v[6:7]
	v_mov_b32_e32 v8, v59
	v_add_f32_e32 v4, v7, v6
	v_cndmask_b32_e32 v3, v4, v3, vcc
	v_and_b32_e32 v7, 0xffff0000, v51
	v_and_b32_e32 v6, 0xffff0000, v47
	v_mov_b32_e32 v4, v55
	v_mul_f32_e32 v3, 0x3e38aa3b, v3
	v_mov_b32_e32 v9, v55
	v_pk_mul_f32 v[10:11], v[8:9], v[6:7]
	v_mov_b32_e32 v5, v59
	v_pk_mul_f32 v[4:5], v[4:5], v[6:7]
	v_cvt_pk_bf16_f32 v3, v3, s0
	v_sub_f32_e32 v8, v10, v11
	v_add_f32_e32 v4, v5, v4
	v_perm_b32 v3, 0, v3, v238
	v_cndmask_b32_e32 v6, v4, v8, vcc

.LBB0_864:
	s_setprio 0
	s_waitcnt vmcnt(0)
	s_waitcnt lgkmcnt(0)
	s_barrier
	s_mov_b64 s[36:37], exec
	v_readlane_b32 s2, v254, 4
	v_readlane_b32 s54, v255, 33
	v_readlane_b32 s3, v254, 5
	v_readlane_b32 s55, v255, 34
	s_and_b64 s[2:3], s[36:37], s[2:3]
	s_movk_i32 s55, 0x5800
	s_mov_b64 exec, s[2:3]
	s_cbranch_execz .LBB0_916
	s_waitcnt vmcnt(0) expcnt(0) lgkmcnt(0)
	ds_read_b32 v2, v221
	ds_read_b32 v0, v222
	s_waitcnt lgkmcnt(1)
	v_cmp_ne_u32_e32 vcc, 0, v2
	s_cbranch_vccnz .LBB0_880
	s_mov_b32 s25, 1
	s_branch .LBB0_868
